# QK gather prefetch depth 7 tiles (8 K buffers) with per-query bias bucket precompute
# baseline (speedup 1.0000x reference)
; #define LAS __attribute__((address_space(3)))
; __device__ __forceinline__ void dsa_unit(int wv, const Args& A, LAS unsigned char* lds, int s, int qt) {
;     ...
;         const int qq = 2 * w + qi2; int n = __builtin_amdgcn_readfirstlane((int)cnt[qq]); n = n > 256 ? 256 : n;
;         const size_t qrow = qrow0 + qq; const int qpos = qpos0 + qq;
;         LAS const unsigned short* lst = ci + qq * CAP;
;         long qf[8];
; #pragma unroll
;         for (int kk = 0; kk < 8; ++kk) { qf[kk] = 0;
;             if (fr < 8 && (fr >> 2) == (kk >> 2)) { const h16x8 q = __builtin_bit_cast(h16x8, *(const u32x4*)(PROJ + qrow * PW + C_Q + fr * 128 + ((kk >> 1) & 1) * 64 + fq * 16 + (kk & 1) * 8));
;                 f32x4 a, bq;
; #pragma unroll
;                 for (int e = 0; e < 4; ++e) { a[e] = 16.f * (float)q[e]; bq[e] = 16.f * (float)q[4 + e]; }
;                 qf[kk] = __builtin_bit_cast(long, pack_fp8x8(a, bq)); } }
;         const int nt = n >> 4;
.LBB0_1429:
	s_or_b32 s1, s0, s94
	s_lshl_b32 s12, s1, 2
	s_add_i32 s12, s12, 0
	s_add_i32 s12, s12, 0x1c800
	v_mov_b32_e32 v0, s12
	ds_read_b32 v0, v0
	s_ashr_i32 s12, s1, 31
	s_add_u32 s22, s1, s5
	s_addc_u32 s23, s12, 0
	s_mul_i32 s14, s23, 0x2e00
	v_mad_u64_u32 v[2:3], s[12:13], s22, v157, v[22:23]
	s_waitcnt lgkmcnt(0)
	v_readfirstlane_b32 s30, v0
	v_add_u32_e32 v3, s14, v3
	v_mov_b64_e32 v[32:33], 0
	v_mov_b64_e32 v[34:35], 0
	v_mov_b64_e32 v[36:37], 0
	v_mov_b64_e32 v[38:39], 0
	v_mov_b64_e32 v[40:41], 0
	v_mov_b64_e32 v[42:43], 0
	v_mov_b64_e32 v[44:45], 0
	v_mov_b64_e32 v[46:47], 0
	s_or_b64 s[14:15], s[10:11], s[20:21]
	s_and_saveexec_b64 s[12:13], s[14:15]
	global_load_dwordx4 v[56:59], v[2:3], off
	global_load_dwordx4 v[60:63], v[2:3], off offset:16
	global_load_dwordx4 v[64:67], v[2:3], off offset:128
	global_load_dwordx4 v[68:71], v[2:3], off offset:144
	s_waitcnt vmcnt(3)
	v_cvt_f32_f16_e32 v145, v56
	v_cvt_f32_f16_e32 v146, v58
	v_cvt_f32_f16_sdwa v147, v56 dst_sel:DWORD dst_unused:UNUSED_PAD src0_sel:WORD_1
	v_cvt_f32_f16_sdwa v148, v58 dst_sel:DWORD dst_unused:UNUSED_PAD src0_sel:WORD_1
	v_mul_f32_e32 v145, 0x41800000, v145
	v_mul_f32_e32 v146, 0x41800000, v146
	v_mul_f32_e32 v147, 0x41800000, v147
	v_mul_f32_e32 v148, 0x41800000, v148
	v_cvt_f32_f16_e32 v149, v57
	v_cvt_f32_f16_e32 v158, v59
	v_cvt_f32_f16_sdwa v159, v57 dst_sel:DWORD dst_unused:UNUSED_PAD src0_sel:WORD_1
	v_cvt_f32_f16_sdwa v160, v59 dst_sel:DWORD dst_unused:UNUSED_PAD src0_sel:WORD_1
	v_cvt_pk_fp8_f32 v72, v145, v147
	v_cvt_pk_fp8_f32 v73, v146, v148
	v_mul_f32_e32 v149, 0x41800000, v149
	v_mul_f32_e32 v158, 0x41800000, v158
	v_mul_f32_e32 v159, 0x41800000, v159
	v_mul_f32_e32 v160, 0x41800000, v160
	v_cvt_pk_fp8_f32 v72, v149, v159 op_sel:[0,0,1]
	v_cvt_pk_fp8_f32 v73, v158, v160 op_sel:[0,0,1]
	s_waitcnt vmcnt(2)
	v_cvt_f32_f16_e32 v145, v60
	v_cvt_f32_f16_e32 v146, v62
	v_cvt_f32_f16_sdwa v147, v60 dst_sel:DWORD dst_unused:UNUSED_PAD src0_sel:WORD_1
	v_cvt_f32_f16_sdwa v148, v62 dst_sel:DWORD dst_unused:UNUSED_PAD src0_sel:WORD_1
	v_mul_f32_e32 v145, 0x41800000, v145
	v_mul_f32_e32 v146, 0x41800000, v146
	v_mul_f32_e32 v147, 0x41800000, v147
	v_mul_f32_e32 v148, 0x41800000, v148
	v_cvt_f32_f16_e32 v149, v61
	v_cvt_f32_f16_e32 v158, v63
	v_cvt_f32_f16_sdwa v159, v61 dst_sel:DWORD dst_unused:UNUSED_PAD src0_sel:WORD_1
	v_cvt_f32_f16_sdwa v160, v63 dst_sel:DWORD dst_unused:UNUSED_PAD src0_sel:WORD_1
	v_cvt_pk_fp8_f32 v74, v145, v147
	v_cvt_pk_fp8_f32 v75, v146, v148
	v_mul_f32_e32 v149, 0x41800000, v149
	v_mul_f32_e32 v158, 0x41800000, v158
	v_mul_f32_e32 v159, 0x41800000, v159
	v_mul_f32_e32 v160, 0x41800000, v160
	v_cvt_pk_fp8_f32 v74, v149, v159 op_sel:[0,0,1]
	v_cvt_pk_fp8_f32 v75, v158, v160 op_sel:[0,0,1]
	s_waitcnt vmcnt(1)
	v_cvt_f32_f16_e32 v145, v64
	v_cvt_f32_f16_e32 v146, v66
	v_cvt_f32_f16_sdwa v147, v64 dst_sel:DWORD dst_unused:UNUSED_PAD src0_sel:WORD_1
	v_cvt_f32_f16_sdwa v148, v66 dst_sel:DWORD dst_unused:UNUSED_PAD src0_sel:WORD_1
	v_mul_f32_e32 v145, 0x41800000, v145
	v_mul_f32_e32 v146, 0x41800000, v146
	v_mul_f32_e32 v147, 0x41800000, v147
	v_mul_f32_e32 v148, 0x41800000, v148
	v_cvt_f32_f16_e32 v149, v65
	v_cvt_f32_f16_e32 v158, v67
	v_cvt_f32_f16_sdwa v159, v65 dst_sel:DWORD dst_unused:UNUSED_PAD src0_sel:WORD_1
	v_cvt_f32_f16_sdwa v160, v67 dst_sel:DWORD dst_unused:UNUSED_PAD src0_sel:WORD_1
	v_cvt_pk_fp8_f32 v76, v145, v147
	v_cvt_pk_fp8_f32 v77, v146, v148
	v_mul_f32_e32 v149, 0x41800000, v149
	v_mul_f32_e32 v158, 0x41800000, v158
	v_mul_f32_e32 v159, 0x41800000, v159
	v_mul_f32_e32 v160, 0x41800000, v160
	v_cvt_pk_fp8_f32 v76, v149, v159 op_sel:[0,0,1]
	v_cvt_pk_fp8_f32 v77, v158, v160 op_sel:[0,0,1]
	s_waitcnt vmcnt(0)
	v_cvt_f32_f16_e32 v145, v68
	v_cvt_f32_f16_e32 v146, v70
	v_cvt_f32_f16_sdwa v147, v68 dst_sel:DWORD dst_unused:UNUSED_PAD src0_sel:WORD_1
	v_cvt_f32_f16_sdwa v148, v70 dst_sel:DWORD dst_unused:UNUSED_PAD src0_sel:WORD_1
	v_mul_f32_e32 v145, 0x41800000, v145
	v_mul_f32_e32 v146, 0x41800000, v146
	v_mul_f32_e32 v147, 0x41800000, v147
	v_mul_f32_e32 v148, 0x41800000, v148
	v_cvt_f32_f16_e32 v149, v69
	v_cvt_f32_f16_e32 v158, v71
	v_cvt_f32_f16_sdwa v159, v69 dst_sel:DWORD dst_unused:UNUSED_PAD src0_sel:WORD_1
	v_cvt_f32_f16_sdwa v160, v71 dst_sel:DWORD dst_unused:UNUSED_PAD src0_sel:WORD_1
	v_cvt_pk_fp8_f32 v78, v145, v147
	v_cvt_pk_fp8_f32 v79, v146, v148
	v_mul_f32_e32 v149, 0x41800000, v149
	v_mul_f32_e32 v158, 0x41800000, v158
	v_mul_f32_e32 v159, 0x41800000, v159
	v_mul_f32_e32 v160, 0x41800000, v160
	v_cvt_pk_fp8_f32 v78, v149, v159 op_sel:[0,0,1]
	v_cvt_pk_fp8_f32 v79, v158, v160 op_sel:[0,0,1]
	s_nop 0
	v_cndmask_b32_e64 v34, 0, v72, s[10:11]
	v_cndmask_b32_e64 v35, 0, v73, s[10:11]
	v_cndmask_b32_e64 v42, 0, v72, s[20:21]
	v_cndmask_b32_e64 v43, 0, v73, s[20:21]
	v_cndmask_b32_e64 v32, 0, v74, s[10:11]
	v_cndmask_b32_e64 v33, 0, v75, s[10:11]
	v_cndmask_b32_e64 v40, 0, v74, s[20:21]
	v_cndmask_b32_e64 v41, 0, v75, s[20:21]
	v_cndmask_b32_e64 v38, 0, v76, s[10:11]
	v_cndmask_b32_e64 v39, 0, v77, s[10:11]
	v_cndmask_b32_e64 v46, 0, v76, s[20:21]
	v_cndmask_b32_e64 v47, 0, v77, s[20:21]
	v_cndmask_b32_e64 v36, 0, v78, s[10:11]
	v_cndmask_b32_e64 v37, 0, v79, s[10:11]
	v_cndmask_b32_e64 v44, 0, v78, s[20:21]
	v_cndmask_b32_e64 v45, 0, v79, s[20:21]
	s_or_b64 exec, exec, s[12:13]
	s_min_i32 s29, s30, 0x100
	s_ashr_i32 s16, s29, 4
	s_cmp_lt_i32 s16, 1
	s_mulk_i32 s0, 0x980
	s_cbranch_scc1 .LBB0_1458
; __device__ __forceinline__ void dsa_unit(int wv, const Args& A, LAS unsigned char* lds, int s, int qt) {
;     ...
;         DSA_LOADT(kf, 0);
;         for (int kt = 0; kt < nt; ++kt) {
;             long k1[8];
;             DSA_LOADT(k1, kt + 1);
	s_mul_i32 s12, s1, 0x980
	s_add_i32 s1, s1, s4
	v_lshl_add_u32 v141, v94, 1, s12
	v_add_u32_e32 v141, 0x13000, v141
	ds_read_u16 v107, v141
	ds_read_u16 v108, v141 offset:32
	ds_read_u16 v109, v141 offset:64
	ds_read_u16 v110, v141 offset:96
	ds_read_u16 v111, v141 offset:128
	ds_read_u16 v112, v141 offset:160
	ds_read_u16 v113, v141 offset:192
	ds_read_u16 v114, v141 offset:224
	ds_read_u16 v115, v141 offset:256
	ds_read_u16 v116, v141 offset:288
	ds_read_u16 v117, v141 offset:320
	ds_read_u16 v118, v141 offset:352
	ds_read_u16 v119, v141 offset:384
	ds_read_u16 v120, v141 offset:416
	ds_read_u16 v121, v141 offset:448
	ds_read_u16 v122, v141 offset:480
	v_mbcnt_lo_u32_b32 v144, -1, 0
	v_mbcnt_hi_u32_b32 v144, -1, v144
	v_lshl_add_u32 v30, v144, 3, s12
	v_add_u32_e32 v30, 0x13000, v30
	ds_read_b64 v[92:93], v30
	s_lshl_b32 s12, s12, 1
	v_lshl_add_u32 v28, v144, 4, s12
	v_add_u32_e32 v143, 0x1cc80, v103
	v_lshrrev_b32_e32 v144, 4, v144
	v_lshlrev_b32_e32 v144, 4, v144
	v_add_u32_e32 v29, s12, v144
	s_waitcnt lgkmcnt(0)
	v_add_lshl_u32 v107, s48, v107, 8
	v_add_u32_e32 v107, v144, v107
	global_load_dwordx4 v[56:59], v107, s[84:85]
	global_load_dwordx4 v[60:63], v107, s[84:85] offset:64
	global_load_dwordx4 v[64:67], v107, s[84:85] offset:128
	global_load_dwordx4 v[68:71], v107, s[84:85] offset:192
	s_cmp_gt_i32 s16, 1
	s_cbranch_scc0 .Lqk_ni_pre
	v_add_lshl_u32 v108, s48, v108, 8
	v_add_u32_e32 v108, v144, v108
	global_load_dwordx4 v[72:75], v108, s[84:85]
	global_load_dwordx4 v[76:79], v108, s[84:85] offset:64
	global_load_dwordx4 v[80:83], v108, s[84:85] offset:128
	global_load_dwordx4 v[84:87], v108, s[84:85] offset:192
	s_cmp_gt_i32 s16, 2
	s_cbranch_scc0 .Lqk_ni_pre
	v_add_lshl_u32 v109, s48, v109, 8
	v_add_u32_e32 v109, v144, v109
	global_load_dwordx4 v[124:127], v109, s[84:85]
	global_load_dwordx4 v[128:131], v109, s[84:85] offset:64
	global_load_dwordx4 v[132:135], v109, s[84:85] offset:128
	global_load_dwordx4 v[136:139], v109, s[84:85] offset:192
	s_cmp_gt_i32 s16, 3
	s_cbranch_scc0 .Lqk_ni_pre
	v_add_lshl_u32 v110, s48, v110, 8
	v_add_u32_e32 v110, v144, v110
	global_load_dwordx4 v[180:183], v110, s[84:85]
	global_load_dwordx4 v[184:187], v110, s[84:85] offset:64
	global_load_dwordx4 v[188:191], v110, s[84:85] offset:128
	global_load_dwordx4 v[192:195], v110, s[84:85] offset:192
	s_cmp_gt_i32 s16, 4
	s_cbranch_scc0 .Lqk_ni_pre
	v_add_lshl_u32 v111, s48, v111, 8
	v_add_u32_e32 v111, v144, v111
	global_load_dwordx4 v[196:199], v111, s[84:85]
	global_load_dwordx4 v[200:203], v111, s[84:85] offset:64
	global_load_dwordx4 v[204:207], v111, s[84:85] offset:128
	global_load_dwordx4 v[208:211], v111, s[84:85] offset:192
	s_cmp_gt_i32 s16, 5
	s_cbranch_scc0 .Lqk_ni_pre
	v_add_lshl_u32 v112, s48, v112, 8
	v_add_u32_e32 v112, v144, v112
	global_load_dwordx4 v[212:215], v112, s[84:85]
	global_load_dwordx4 v[216:219], v112, s[84:85] offset:64
	global_load_dwordx4 v[220:223], v112, s[84:85] offset:128
	global_load_dwordx4 v[224:227], v112, s[84:85] offset:192
	s_cmp_gt_i32 s16, 6
	s_cbranch_scc0 .Lqk_ni_pre
	v_add_lshl_u32 v113, s48, v113, 8
	v_add_u32_e32 v113, v144, v113
	global_load_dwordx4 v[240:243], v113, s[84:85]
	global_load_dwordx4 v[244:247], v113, s[84:85] offset:64
	global_load_dwordx4 v[248:251], v113, s[84:85] offset:128
	global_load_dwordx4 v[252:255], v113, s[84:85] offset:192
.Lqk_ni_pre:
	v_and_b32_e32 v145, 0xffff, v92
	v_lshrrev_b32_e32 v146, 16, v92
	v_and_b32_e32 v147, 0xffff, v93
	v_lshrrev_b32_e32 v148, 16, v93
	v_subrev_u32_e32 v145, s1, v145
	v_subrev_u32_e32 v146, s1, v146
	v_subrev_u32_e32 v147, s1, v147
	v_subrev_u32_e32 v148, s1, v148
	v_sub_u32_e32 v149, 0, v145
	v_sub_u32_e32 v158, 0, v146
	v_sub_u32_e32 v159, 0, v147
	v_sub_u32_e32 v160, 0, v148
	v_max_i32_e32 v149, v145, v149
	v_max_i32_e32 v158, v146, v158
	v_max_i32_e32 v159, v147, v159
	v_max_i32_e32 v160, v148, v160
	v_mul_u32_u24_e32 v161, v149, v149
	v_mul_u32_u24_e32 v162, v158, v158
	v_mul_u32_u24_e32 v163, v159, v159
	v_mul_u32_u24_e32 v164, v160, v160
	v_cvt_f32_u32_e32 v161, v161
	v_cvt_f32_u32_e32 v162, v162
	v_cvt_f32_u32_e32 v163, v163
	v_cvt_f32_u32_e32 v164, v164
	v_lshrrev_b32_e32 v161, 23, v161
	v_lshrrev_b32_e32 v162, 23, v162
	v_lshrrev_b32_e32 v163, 23, v163
	v_lshrrev_b32_e32 v164, 23, v164
	v_add_u32_e32 v161, 0xffffff83, v161
	v_add_u32_e32 v162, 0xffffff83, v162
	v_add_u32_e32 v163, 0xffffff83, v163
	v_add_u32_e32 v164, 0xffffff83, v164
	v_min_u32_e32 v161, 15, v161
	v_min_u32_e32 v162, 15, v162
	v_min_u32_e32 v163, 15, v163
	v_min_u32_e32 v164, 15, v164
	v_cmp_gt_u32_e32 vcc, 8, v149
	v_cmp_gt_u32_e64 s[26:27], 8, v158
	v_cmp_gt_u32_e64 s[36:37], 8, v159
	v_cmp_gt_u32_e64 s[38:39], 8, v160
	v_med3_i32 v165, v145, 0, 1
	v_med3_i32 v166, v146, 0, 1
	v_med3_i32 v167, v147, 0, 1
	v_med3_i32 v168, v148, 0, 1
	v_cndmask_b32_e64 v161, v161, v149, vcc
	v_cndmask_b32_e64 v162, v162, v158, s[26:27]
	v_cndmask_b32_e64 v163, v163, v159, s[36:37]
	v_cndmask_b32_e64 v164, v164, v160, s[38:39]
	v_lshl_add_u32 v161, v165, 4, v161
	v_lshl_add_u32 v162, v166, 4, v162
	v_lshl_add_u32 v163, v167, 4, v163
	v_lshl_add_u32 v164, v168, 4, v164
	v_lshlrev_b32_e32 v48, 5, v161
	v_lshlrev_b32_e32 v49, 5, v162
	v_lshlrev_b32_e32 v50, 5, v163
	v_lshlrev_b32_e32 v51, 5, v164
	ds_write_b128 v28, v[48:51]
	ds_read_b128 v[52:55], v29
	s_cmp_gt_i32 s16, 7
	s_cbranch_scc0 .Lqk_n7_0
	v_add_lshl_u32 v114, s48, v114, 8
	v_add_u32_e32 v114, v144, v114
	global_load_dwordx4 v[4:7], v114, s[84:85]
	global_load_dwordx4 v[8:11], v114, s[84:85] offset:64
	global_load_dwordx4 v[12:15], v114, s[84:85] offset:128
	global_load_dwordx4 v[16:19], v114, s[84:85] offset:192
	s_waitcnt vmcnt(28)
	s_branch .Lqk_go_0
.Lqk_n7_0:
	s_cmp_gt_i32 s16, 6
	s_cbranch_scc0 .Lqk_n6_0
	s_waitcnt vmcnt(24)
	s_branch .Lqk_go_0

; __device__ __forceinline__ void dsa_unit(int wv, const Args& A, LAS unsigned char* lds, int s, int qt) {
;     ...
;         for (int kt = 0; kt < nt; ++kt) {
;             long k1[8];
;             DSA_LOADT(k1, kt + 1);
;             f32x4 a = {0.f, 0.f, 0.f, 0.f};
; #pragma unroll
;             for (int kk = 0; kk < 8; ++kk) a = __builtin_amdgcn_mfma_f32_16x16x32_fp8_fp8(kf[kk], qf[kk], a, 0, 0, 0);
;             if (fr < 8) {
; #pragma unroll
;                 for (int r = 0; r < 4; ++r) { const int e2 = kt * 16 + fq * 4 + r; const int key2 = lst[e2];
;                     Pw[e2 * 8 + fr] = (h16)(a[r] * 0.0625f + relb[rel_bucket(key2 - qpos) * 8 + fr]); } }
; #pragma unroll
;             for (int kk = 0; kk < 8; ++kk) kf[kk] = k1[kk];
.Lqk_go_0:
	v_mfma_f32_16x16x32_fp8_fp8 v[88:91], v[56:57], v[34:35], 0
	v_mfma_f32_16x16x32_fp8_fp8 v[88:91], v[58:59], v[32:33], v[88:91]
	v_mfma_f32_16x16x32_fp8_fp8 v[88:91], v[60:61], v[38:39], v[88:91]
	v_mfma_f32_16x16x32_fp8_fp8 v[88:91], v[62:63], v[36:37], v[88:91]
	v_mfma_f32_16x16x32_fp8_fp8 v[88:91], v[64:65], v[42:43], v[88:91]
	v_mfma_f32_16x16x32_fp8_fp8 v[88:91], v[66:67], v[40:41], v[88:91]
	v_mfma_f32_16x16x32_fp8_fp8 v[88:91], v[68:69], v[46:47], v[88:91]
	v_mfma_f32_16x16x32_fp8_fp8 v[88:91], v[70:71], v[44:45], v[88:91]
	s_and_saveexec_b64 s[12:13], s[8:9]
	s_waitcnt lgkmcnt(0)
	v_add_u32_e32 v165, v52, v25
	v_add_u32_e32 v166, v53, v25
	v_add_u32_e32 v167, v54, v25
	v_add_u32_e32 v168, v55, v25
	ds_read_b32 v165, v165
	ds_read_b32 v166, v166
	ds_read_b32 v167, v167
	ds_read_b32 v168, v168
	s_waitcnt lgkmcnt(3)
	v_fma_mixlo_f16 v165, v88, s3, v165
	s_waitcnt lgkmcnt(2)
	v_fma_mixlo_f16 v166, v89, s3, v166
	s_waitcnt lgkmcnt(1)
	v_fma_mixlo_f16 v167, v90, s3, v167
	s_waitcnt lgkmcnt(0)
	v_fma_mixlo_f16 v168, v91, s3, v168
	ds_write_b16 v143, v165
	ds_write_b16 v143, v166 offset:16
	ds_write_b16 v143, v167 offset:32
	ds_write_b16 v143, v168 offset:48
	s_mov_b64 exec, s[12:13]
	s_cmp_le_i32 s16, 1
	s_cbranch_scc1 .Lqk_done
	ds_read_b128 v[52:55], v29 offset:64
	s_cmp_gt_i32 s16, 8
	s_cbranch_scc0 .Lqk_n7_1
	v_add_lshl_u32 v115, s48, v115, 8
	v_add_u32_e32 v115, v144, v115
	global_load_dwordx4 v[56:59], v115, s[84:85]
	global_load_dwordx4 v[60:63], v115, s[84:85] offset:64
	global_load_dwordx4 v[64:67], v115, s[84:85] offset:128
	global_load_dwordx4 v[68:71], v115, s[84:85] offset:192
	s_waitcnt vmcnt(28)
	s_branch .Lqk_go_1
.Lqk_n7_1:
	s_cmp_gt_i32 s16, 7
	s_cbranch_scc0 .Lqk_n6_1
	s_waitcnt vmcnt(24)
	s_branch .Lqk_go_1

; __device__ __forceinline__ void dsa_unit(int wv, const Args& A, LAS unsigned char* lds, int s, int qt) {
;     ...
;         for (int kt = 0; kt < nt; ++kt) {
;             long k1[8];
;             DSA_LOADT(k1, kt + 1);
;             f32x4 a = {0.f, 0.f, 0.f, 0.f};
; #pragma unroll
;             for (int kk = 0; kk < 8; ++kk) a = __builtin_amdgcn_mfma_f32_16x16x32_fp8_fp8(kf[kk], qf[kk], a, 0, 0, 0);
;             if (fr < 8) {
; #pragma unroll
;                 for (int r = 0; r < 4; ++r) { const int e2 = kt * 16 + fq * 4 + r; const int key2 = lst[e2];
;                     Pw[e2 * 8 + fr] = (h16)(a[r] * 0.0625f + relb[rel_bucket(key2 - qpos) * 8 + fr]); } }
; #pragma unroll
;             for (int kk = 0; kk < 8; ++kk) kf[kk] = k1[kk];
.Lqk_go_1:
	v_mfma_f32_16x16x32_fp8_fp8 v[88:91], v[72:73], v[34:35], 0
	v_mfma_f32_16x16x32_fp8_fp8 v[88:91], v[74:75], v[32:33], v[88:91]
	v_mfma_f32_16x16x32_fp8_fp8 v[88:91], v[76:77], v[38:39], v[88:91]
	v_mfma_f32_16x16x32_fp8_fp8 v[88:91], v[78:79], v[36:37], v[88:91]
	v_mfma_f32_16x16x32_fp8_fp8 v[88:91], v[80:81], v[42:43], v[88:91]
	v_mfma_f32_16x16x32_fp8_fp8 v[88:91], v[82:83], v[40:41], v[88:91]
	v_mfma_f32_16x16x32_fp8_fp8 v[88:91], v[84:85], v[46:47], v[88:91]
	v_mfma_f32_16x16x32_fp8_fp8 v[88:91], v[86:87], v[44:45], v[88:91]
	s_and_saveexec_b64 s[12:13], s[8:9]
	s_waitcnt lgkmcnt(0)
	v_add_u32_e32 v165, v52, v25
	v_add_u32_e32 v166, v53, v25
	v_add_u32_e32 v167, v54, v25
	v_add_u32_e32 v168, v55, v25
	ds_read_b32 v165, v165
	ds_read_b32 v166, v166
	ds_read_b32 v167, v167
	ds_read_b32 v168, v168
	s_waitcnt lgkmcnt(3)
	v_fma_mixlo_f16 v165, v88, s3, v165
	s_waitcnt lgkmcnt(2)
	v_fma_mixlo_f16 v166, v89, s3, v166
	s_waitcnt lgkmcnt(1)
	v_fma_mixlo_f16 v167, v90, s3, v167
	s_waitcnt lgkmcnt(0)
	v_fma_mixlo_f16 v168, v91, s3, v168
	ds_write_b16 v143, v165 offset:256
	ds_write_b16 v143, v166 offset:272
	ds_write_b16 v143, v167 offset:288
	ds_write_b16 v143, v168 offset:304
	s_mov_b64 exec, s[12:13]
	s_cmp_le_i32 s16, 2
	s_cbranch_scc1 .Lqk_done
	ds_read_b128 v[52:55], v29 offset:128
	s_cmp_gt_i32 s16, 9
	s_cbranch_scc0 .Lqk_n7_2
	v_add_lshl_u32 v116, s48, v116, 8
	v_add_u32_e32 v116, v144, v116
	global_load_dwordx4 v[72:75], v116, s[84:85]
	global_load_dwordx4 v[76:79], v116, s[84:85] offset:64
	global_load_dwordx4 v[80:83], v116, s[84:85] offset:128
	global_load_dwordx4 v[84:87], v116, s[84:85] offset:192
	s_waitcnt vmcnt(28)
	s_branch .Lqk_go_2
.Lqk_n7_2:
	s_cmp_gt_i32 s16, 8
	s_cbranch_scc0 .Lqk_n6_2
	s_waitcnt vmcnt(24)
	s_branch .Lqk_go_2

; __device__ __forceinline__ void dsa_unit(int wv, const Args& A, LAS unsigned char* lds, int s, int qt) {
;     ...
;         for (int kt = 0; kt < nt; ++kt) {
;             long k1[8];
;             DSA_LOADT(k1, kt + 1);
;             f32x4 a = {0.f, 0.f, 0.f, 0.f};
; #pragma unroll
;             for (int kk = 0; kk < 8; ++kk) a = __builtin_amdgcn_mfma_f32_16x16x32_fp8_fp8(kf[kk], qf[kk], a, 0, 0, 0);
;             if (fr < 8) {
; #pragma unroll
;                 for (int r = 0; r < 4; ++r) { const int e2 = kt * 16 + fq * 4 + r; const int key2 = lst[e2];
;                     Pw[e2 * 8 + fr] = (h16)(a[r] * 0.0625f + relb[rel_bucket(key2 - qpos) * 8 + fr]); } }
; #pragma unroll
;             for (int kk = 0; kk < 8; ++kk) kf[kk] = k1[kk];
.Lqk_go_2:
	v_mfma_f32_16x16x32_fp8_fp8 v[88:91], v[124:125], v[34:35], 0
	v_mfma_f32_16x16x32_fp8_fp8 v[88:91], v[126:127], v[32:33], v[88:91]
	v_mfma_f32_16x16x32_fp8_fp8 v[88:91], v[128:129], v[38:39], v[88:91]
	v_mfma_f32_16x16x32_fp8_fp8 v[88:91], v[130:131], v[36:37], v[88:91]
	v_mfma_f32_16x16x32_fp8_fp8 v[88:91], v[132:133], v[42:43], v[88:91]
	v_mfma_f32_16x16x32_fp8_fp8 v[88:91], v[134:135], v[40:41], v[88:91]
	v_mfma_f32_16x16x32_fp8_fp8 v[88:91], v[136:137], v[46:47], v[88:91]
	v_mfma_f32_16x16x32_fp8_fp8 v[88:91], v[138:139], v[44:45], v[88:91]
	s_and_saveexec_b64 s[12:13], s[8:9]
	s_waitcnt lgkmcnt(0)
	v_add_u32_e32 v165, v52, v25
	v_add_u32_e32 v166, v53, v25
	v_add_u32_e32 v167, v54, v25
	v_add_u32_e32 v168, v55, v25
	ds_read_b32 v165, v165
	ds_read_b32 v166, v166
	ds_read_b32 v167, v167
	ds_read_b32 v168, v168
	s_waitcnt lgkmcnt(3)
	v_fma_mixlo_f16 v165, v88, s3, v165
	s_waitcnt lgkmcnt(2)
	v_fma_mixlo_f16 v166, v89, s3, v166
	s_waitcnt lgkmcnt(1)
	v_fma_mixlo_f16 v167, v90, s3, v167
	s_waitcnt lgkmcnt(0)
	v_fma_mixlo_f16 v168, v91, s3, v168
	ds_write_b16 v143, v165 offset:512
	ds_write_b16 v143, v166 offset:528
	ds_write_b16 v143, v167 offset:544
	ds_write_b16 v143, v168 offset:560
	s_mov_b64 exec, s[12:13]
	s_cmp_le_i32 s16, 3
	s_cbranch_scc1 .Lqk_done
	ds_read_b128 v[52:55], v29 offset:192
	s_cmp_gt_i32 s16, 10
	s_cbranch_scc0 .Lqk_n7_3
	v_add_lshl_u32 v117, s48, v117, 8
	v_add_u32_e32 v117, v144, v117
	global_load_dwordx4 v[124:127], v117, s[84:85]
	global_load_dwordx4 v[128:131], v117, s[84:85] offset:64
	global_load_dwordx4 v[132:135], v117, s[84:85] offset:128
	global_load_dwordx4 v[136:139], v117, s[84:85] offset:192
	s_waitcnt vmcnt(28)
	s_branch .Lqk_go_3
.Lqk_n7_3:
	s_cmp_gt_i32 s16, 9
	s_cbranch_scc0 .Lqk_n6_3
	s_waitcnt vmcnt(24)
	s_branch .Lqk_go_3

; __device__ __forceinline__ void dsa_unit(int wv, const Args& A, LAS unsigned char* lds, int s, int qt) {
;     ...
;         for (int kt = 0; kt < nt; ++kt) {
;             long k1[8];
;             DSA_LOADT(k1, kt + 1);
;             f32x4 a = {0.f, 0.f, 0.f, 0.f};
; #pragma unroll
;             for (int kk = 0; kk < 8; ++kk) a = __builtin_amdgcn_mfma_f32_16x16x32_fp8_fp8(kf[kk], qf[kk], a, 0, 0, 0);
;             if (fr < 8) {
; #pragma unroll
;                 for (int r = 0; r < 4; ++r) { const int e2 = kt * 16 + fq * 4 + r; const int key2 = lst[e2];
;                     Pw[e2 * 8 + fr] = (h16)(a[r] * 0.0625f + relb[rel_bucket(key2 - qpos) * 8 + fr]); } }
; #pragma unroll
;             for (int kk = 0; kk < 8; ++kk) kf[kk] = k1[kk];
.Lqk_go_3:
	v_mfma_f32_16x16x32_fp8_fp8 v[88:91], v[180:181], v[34:35], 0
	v_mfma_f32_16x16x32_fp8_fp8 v[88:91], v[182:183], v[32:33], v[88:91]
	v_mfma_f32_16x16x32_fp8_fp8 v[88:91], v[184:185], v[38:39], v[88:91]
	v_mfma_f32_16x16x32_fp8_fp8 v[88:91], v[186:187], v[36:37], v[88:91]
	v_mfma_f32_16x16x32_fp8_fp8 v[88:91], v[188:189], v[42:43], v[88:91]
	v_mfma_f32_16x16x32_fp8_fp8 v[88:91], v[190:191], v[40:41], v[88:91]
	v_mfma_f32_16x16x32_fp8_fp8 v[88:91], v[192:193], v[46:47], v[88:91]
	v_mfma_f32_16x16x32_fp8_fp8 v[88:91], v[194:195], v[44:45], v[88:91]
	s_and_saveexec_b64 s[12:13], s[8:9]
	s_waitcnt lgkmcnt(0)
	v_add_u32_e32 v165, v52, v25
	v_add_u32_e32 v166, v53, v25
	v_add_u32_e32 v167, v54, v25
	v_add_u32_e32 v168, v55, v25
	ds_read_b32 v165, v165
	ds_read_b32 v166, v166
	ds_read_b32 v167, v167
	ds_read_b32 v168, v168
	s_waitcnt lgkmcnt(3)
	v_fma_mixlo_f16 v165, v88, s3, v165
	s_waitcnt lgkmcnt(2)
	v_fma_mixlo_f16 v166, v89, s3, v166
	s_waitcnt lgkmcnt(1)
	v_fma_mixlo_f16 v167, v90, s3, v167
	s_waitcnt lgkmcnt(0)
	v_fma_mixlo_f16 v168, v91, s3, v168
	ds_write_b16 v143, v165 offset:768
	ds_write_b16 v143, v166 offset:784
	ds_write_b16 v143, v167 offset:800
	ds_write_b16 v143, v168 offset:816
	s_mov_b64 exec, s[12:13]
	s_cmp_le_i32 s16, 4
	s_cbranch_scc1 .Lqk_done
	ds_read_b128 v[52:55], v29 offset:256
	s_cmp_gt_i32 s16, 11
	s_cbranch_scc0 .Lqk_n7_4
	v_add_lshl_u32 v118, s48, v118, 8
	v_add_u32_e32 v118, v144, v118
	global_load_dwordx4 v[180:183], v118, s[84:85]
	global_load_dwordx4 v[184:187], v118, s[84:85] offset:64
	global_load_dwordx4 v[188:191], v118, s[84:85] offset:128
	global_load_dwordx4 v[192:195], v118, s[84:85] offset:192
	s_waitcnt vmcnt(28)
	s_branch .Lqk_go_4
.Lqk_n7_4:
	s_cmp_gt_i32 s16, 10
	s_cbranch_scc0 .Lqk_n6_4
	s_waitcnt vmcnt(24)
	s_branch .Lqk_go_4

; __device__ __forceinline__ void dsa_unit(int wv, const Args& A, LAS unsigned char* lds, int s, int qt) {
;     ...
;         for (int kt = 0; kt < nt; ++kt) {
;             long k1[8];
;             DSA_LOADT(k1, kt + 1);
;             f32x4 a = {0.f, 0.f, 0.f, 0.f};
; #pragma unroll
;             for (int kk = 0; kk < 8; ++kk) a = __builtin_amdgcn_mfma_f32_16x16x32_fp8_fp8(kf[kk], qf[kk], a, 0, 0, 0);
;             if (fr < 8) {
; #pragma unroll
;                 for (int r = 0; r < 4; ++r) { const int e2 = kt * 16 + fq * 4 + r; const int key2 = lst[e2];
;                     Pw[e2 * 8 + fr] = (h16)(a[r] * 0.0625f + relb[rel_bucket(key2 - qpos) * 8 + fr]); } }
; #pragma unroll
;             for (int kk = 0; kk < 8; ++kk) kf[kk] = k1[kk];
.Lqk_go_4:
	v_mfma_f32_16x16x32_fp8_fp8 v[88:91], v[196:197], v[34:35], 0
	v_mfma_f32_16x16x32_fp8_fp8 v[88:91], v[198:199], v[32:33], v[88:91]
	v_mfma_f32_16x16x32_fp8_fp8 v[88:91], v[200:201], v[38:39], v[88:91]
	v_mfma_f32_16x16x32_fp8_fp8 v[88:91], v[202:203], v[36:37], v[88:91]
	v_mfma_f32_16x16x32_fp8_fp8 v[88:91], v[204:205], v[42:43], v[88:91]
	v_mfma_f32_16x16x32_fp8_fp8 v[88:91], v[206:207], v[40:41], v[88:91]
	v_mfma_f32_16x16x32_fp8_fp8 v[88:91], v[208:209], v[46:47], v[88:91]
	v_mfma_f32_16x16x32_fp8_fp8 v[88:91], v[210:211], v[44:45], v[88:91]
	s_and_saveexec_b64 s[12:13], s[8:9]
	s_waitcnt lgkmcnt(0)
	v_add_u32_e32 v165, v52, v25
	v_add_u32_e32 v166, v53, v25
	v_add_u32_e32 v167, v54, v25
	v_add_u32_e32 v168, v55, v25
	ds_read_b32 v165, v165
	ds_read_b32 v166, v166
	ds_read_b32 v167, v167
	ds_read_b32 v168, v168
	s_waitcnt lgkmcnt(3)
	v_fma_mixlo_f16 v165, v88, s3, v165
	s_waitcnt lgkmcnt(2)
	v_fma_mixlo_f16 v166, v89, s3, v166
	s_waitcnt lgkmcnt(1)
	v_fma_mixlo_f16 v167, v90, s3, v167
	s_waitcnt lgkmcnt(0)
	v_fma_mixlo_f16 v168, v91, s3, v168
	ds_write_b16 v143, v165 offset:1024
	ds_write_b16 v143, v166 offset:1040
	ds_write_b16 v143, v167 offset:1056
	ds_write_b16 v143, v168 offset:1072
	s_mov_b64 exec, s[12:13]
	s_cmp_le_i32 s16, 5
	s_cbranch_scc1 .Lqk_done
	ds_read_b128 v[52:55], v29 offset:320
	s_cmp_gt_i32 s16, 12
	s_cbranch_scc0 .Lqk_n7_5
	v_add_lshl_u32 v119, s48, v119, 8
	v_add_u32_e32 v119, v144, v119
	global_load_dwordx4 v[196:199], v119, s[84:85]
	global_load_dwordx4 v[200:203], v119, s[84:85] offset:64
	global_load_dwordx4 v[204:207], v119, s[84:85] offset:128
	global_load_dwordx4 v[208:211], v119, s[84:85] offset:192
	s_waitcnt vmcnt(28)
	s_branch .Lqk_go_5
.Lqk_n7_5:
	s_cmp_gt_i32 s16, 11
	s_cbranch_scc0 .Lqk_n6_5
	s_waitcnt vmcnt(24)
	s_branch .Lqk_go_5

; __device__ __forceinline__ void dsa_unit(int wv, const Args& A, LAS unsigned char* lds, int s, int qt) {
;     ...
;         for (int kt = 0; kt < nt; ++kt) {
;             long k1[8];
;             DSA_LOADT(k1, kt + 1);
;             f32x4 a = {0.f, 0.f, 0.f, 0.f};
; #pragma unroll
;             for (int kk = 0; kk < 8; ++kk) a = __builtin_amdgcn_mfma_f32_16x16x32_fp8_fp8(kf[kk], qf[kk], a, 0, 0, 0);
;             if (fr < 8) {
; #pragma unroll
;                 for (int r = 0; r < 4; ++r) { const int e2 = kt * 16 + fq * 4 + r; const int key2 = lst[e2];
;                     Pw[e2 * 8 + fr] = (h16)(a[r] * 0.0625f + relb[rel_bucket(key2 - qpos) * 8 + fr]); } }
; #pragma unroll
;             for (int kk = 0; kk < 8; ++kk) kf[kk] = k1[kk];
.Lqk_go_5:
	v_mfma_f32_16x16x32_fp8_fp8 v[88:91], v[212:213], v[34:35], 0
	v_mfma_f32_16x16x32_fp8_fp8 v[88:91], v[214:215], v[32:33], v[88:91]
	v_mfma_f32_16x16x32_fp8_fp8 v[88:91], v[216:217], v[38:39], v[88:91]
	v_mfma_f32_16x16x32_fp8_fp8 v[88:91], v[218:219], v[36:37], v[88:91]
	v_mfma_f32_16x16x32_fp8_fp8 v[88:91], v[220:221], v[42:43], v[88:91]
	v_mfma_f32_16x16x32_fp8_fp8 v[88:91], v[222:223], v[40:41], v[88:91]
	v_mfma_f32_16x16x32_fp8_fp8 v[88:91], v[224:225], v[46:47], v[88:91]
	v_mfma_f32_16x16x32_fp8_fp8 v[88:91], v[226:227], v[44:45], v[88:91]
	s_and_saveexec_b64 s[12:13], s[8:9]
	s_waitcnt lgkmcnt(0)
	v_add_u32_e32 v165, v52, v25
	v_add_u32_e32 v166, v53, v25
	v_add_u32_e32 v167, v54, v25
	v_add_u32_e32 v168, v55, v25
	ds_read_b32 v165, v165
	ds_read_b32 v166, v166
	ds_read_b32 v167, v167
	ds_read_b32 v168, v168
	s_waitcnt lgkmcnt(3)
	v_fma_mixlo_f16 v165, v88, s3, v165
	s_waitcnt lgkmcnt(2)
	v_fma_mixlo_f16 v166, v89, s3, v166
	s_waitcnt lgkmcnt(1)
	v_fma_mixlo_f16 v167, v90, s3, v167
	s_waitcnt lgkmcnt(0)
	v_fma_mixlo_f16 v168, v91, s3, v168
	ds_write_b16 v143, v165 offset:1280
	ds_write_b16 v143, v166 offset:1296
	ds_write_b16 v143, v167 offset:1312
	ds_write_b16 v143, v168 offset:1328
	s_mov_b64 exec, s[12:13]
	s_cmp_le_i32 s16, 6
	s_cbranch_scc1 .Lqk_done
	ds_read_b128 v[52:55], v29 offset:384
	s_cmp_gt_i32 s16, 13
	s_cbranch_scc0 .Lqk_n7_6
	v_add_lshl_u32 v120, s48, v120, 8
	v_add_u32_e32 v120, v144, v120
	global_load_dwordx4 v[212:215], v120, s[84:85]
	global_load_dwordx4 v[216:219], v120, s[84:85] offset:64
	global_load_dwordx4 v[220:223], v120, s[84:85] offset:128
	global_load_dwordx4 v[224:227], v120, s[84:85] offset:192
	s_waitcnt vmcnt(28)
	s_branch .Lqk_go_6
.Lqk_n7_6:
	s_cmp_gt_i32 s16, 12
	s_cbranch_scc0 .Lqk_n6_6
	s_waitcnt vmcnt(24)
	s_branch .Lqk_go_6

; __device__ __forceinline__ void dsa_unit(int wv, const Args& A, LAS unsigned char* lds, int s, int qt) {
;     ...
;         for (int kt = 0; kt < nt; ++kt) {
;             long k1[8];
;             DSA_LOADT(k1, kt + 1);
;             f32x4 a = {0.f, 0.f, 0.f, 0.f};
; #pragma unroll
;             for (int kk = 0; kk < 8; ++kk) a = __builtin_amdgcn_mfma_f32_16x16x32_fp8_fp8(kf[kk], qf[kk], a, 0, 0, 0);
;             if (fr < 8) {
; #pragma unroll
;                 for (int r = 0; r < 4; ++r) { const int e2 = kt * 16 + fq * 4 + r; const int key2 = lst[e2];
;                     Pw[e2 * 8 + fr] = (h16)(a[r] * 0.0625f + relb[rel_bucket(key2 - qpos) * 8 + fr]); } }
; #pragma unroll
;             for (int kk = 0; kk < 8; ++kk) kf[kk] = k1[kk];
.Lqk_go_6:
	v_mfma_f32_16x16x32_fp8_fp8 v[88:91], v[240:241], v[34:35], 0
	v_mfma_f32_16x16x32_fp8_fp8 v[88:91], v[242:243], v[32:33], v[88:91]
	v_mfma_f32_16x16x32_fp8_fp8 v[88:91], v[244:245], v[38:39], v[88:91]
	v_mfma_f32_16x16x32_fp8_fp8 v[88:91], v[246:247], v[36:37], v[88:91]
	v_mfma_f32_16x16x32_fp8_fp8 v[88:91], v[248:249], v[42:43], v[88:91]
	v_mfma_f32_16x16x32_fp8_fp8 v[88:91], v[250:251], v[40:41], v[88:91]
	v_mfma_f32_16x16x32_fp8_fp8 v[88:91], v[252:253], v[46:47], v[88:91]
	v_mfma_f32_16x16x32_fp8_fp8 v[88:91], v[254:255], v[44:45], v[88:91]
	s_and_saveexec_b64 s[12:13], s[8:9]
	s_waitcnt lgkmcnt(0)
	v_add_u32_e32 v165, v52, v25
	v_add_u32_e32 v166, v53, v25
	v_add_u32_e32 v167, v54, v25
	v_add_u32_e32 v168, v55, v25
	ds_read_b32 v165, v165
	ds_read_b32 v166, v166
	ds_read_b32 v167, v167
	ds_read_b32 v168, v168
	s_waitcnt lgkmcnt(3)
	v_fma_mixlo_f16 v165, v88, s3, v165
	s_waitcnt lgkmcnt(2)
	v_fma_mixlo_f16 v166, v89, s3, v166
	s_waitcnt lgkmcnt(1)
	v_fma_mixlo_f16 v167, v90, s3, v167
	s_waitcnt lgkmcnt(0)
	v_fma_mixlo_f16 v168, v91, s3, v168
	ds_write_b16 v143, v165 offset:1536
	ds_write_b16 v143, v166 offset:1552
	ds_write_b16 v143, v167 offset:1568
	ds_write_b16 v143, v168 offset:1584
	s_mov_b64 exec, s[12:13]
	s_cmp_le_i32 s16, 7
	s_cbranch_scc1 .Lqk_done
	ds_read_b128 v[52:55], v29 offset:448
	s_cmp_gt_i32 s16, 14
	s_cbranch_scc0 .Lqk_n7_7
	v_add_lshl_u32 v121, s48, v121, 8
	v_add_u32_e32 v121, v144, v121
	global_load_dwordx4 v[240:243], v121, s[84:85]
	global_load_dwordx4 v[244:247], v121, s[84:85] offset:64
	global_load_dwordx4 v[248:251], v121, s[84:85] offset:128
	global_load_dwordx4 v[252:255], v121, s[84:85] offset:192
	s_waitcnt vmcnt(28)
	s_branch .Lqk_go_7
.Lqk_n7_7:
	s_cmp_gt_i32 s16, 13
	s_cbranch_scc0 .Lqk_n6_7
	s_waitcnt vmcnt(24)
	s_branch .Lqk_go_7

; __device__ __forceinline__ void dsa_unit(int wv, const Args& A, LAS unsigned char* lds, int s, int qt) {
;     ...
;         for (int kt = 0; kt < nt; ++kt) {
;             long k1[8];
;             DSA_LOADT(k1, kt + 1);
;             f32x4 a = {0.f, 0.f, 0.f, 0.f};
; #pragma unroll
;             for (int kk = 0; kk < 8; ++kk) a = __builtin_amdgcn_mfma_f32_16x16x32_fp8_fp8(kf[kk], qf[kk], a, 0, 0, 0);
;             if (fr < 8) {
; #pragma unroll
;                 for (int r = 0; r < 4; ++r) { const int e2 = kt * 16 + fq * 4 + r; const int key2 = lst[e2];
;                     Pw[e2 * 8 + fr] = (h16)(a[r] * 0.0625f + relb[rel_bucket(key2 - qpos) * 8 + fr]); } }
; #pragma unroll
;             for (int kk = 0; kk < 8; ++kk) kf[kk] = k1[kk];
.Lqk_go_7:
	v_mfma_f32_16x16x32_fp8_fp8 v[88:91], v[4:5], v[34:35], 0
	v_mfma_f32_16x16x32_fp8_fp8 v[88:91], v[6:7], v[32:33], v[88:91]
	v_mfma_f32_16x16x32_fp8_fp8 v[88:91], v[8:9], v[38:39], v[88:91]
	v_mfma_f32_16x16x32_fp8_fp8 v[88:91], v[10:11], v[36:37], v[88:91]
	v_mfma_f32_16x16x32_fp8_fp8 v[88:91], v[12:13], v[42:43], v[88:91]
	v_mfma_f32_16x16x32_fp8_fp8 v[88:91], v[14:15], v[40:41], v[88:91]
	v_mfma_f32_16x16x32_fp8_fp8 v[88:91], v[16:17], v[46:47], v[88:91]
	v_mfma_f32_16x16x32_fp8_fp8 v[88:91], v[18:19], v[44:45], v[88:91]
	s_and_saveexec_b64 s[12:13], s[8:9]
	s_waitcnt lgkmcnt(0)
	v_add_u32_e32 v165, v52, v25
	v_add_u32_e32 v166, v53, v25
	v_add_u32_e32 v167, v54, v25
	v_add_u32_e32 v168, v55, v25
	ds_read_b32 v165, v165
	ds_read_b32 v166, v166
	ds_read_b32 v167, v167
	ds_read_b32 v168, v168
	s_waitcnt lgkmcnt(3)
	v_fma_mixlo_f16 v165, v88, s3, v165
	s_waitcnt lgkmcnt(2)
	v_fma_mixlo_f16 v166, v89, s3, v166
	s_waitcnt lgkmcnt(1)
	v_fma_mixlo_f16 v167, v90, s3, v167
	s_waitcnt lgkmcnt(0)
	v_fma_mixlo_f16 v168, v91, s3, v168
	ds_write_b16 v143, v165 offset:1792
	ds_write_b16 v143, v166 offset:1808
	ds_write_b16 v143, v167 offset:1824
	ds_write_b16 v143, v168 offset:1840
	s_mov_b64 exec, s[12:13]
	s_cmp_le_i32 s16, 8
	s_cbranch_scc1 .Lqk_done
	ds_read_b128 v[52:55], v29 offset:512
	s_cmp_gt_i32 s16, 15
	s_cbranch_scc0 .Lqk_n7_8
	v_add_lshl_u32 v122, s48, v122, 8
	v_add_u32_e32 v122, v144, v122
	global_load_dwordx4 v[4:7], v122, s[84:85]
	global_load_dwordx4 v[8:11], v122, s[84:85] offset:64
	global_load_dwordx4 v[12:15], v122, s[84:85] offset:128
	global_load_dwordx4 v[16:19], v122, s[84:85] offset:192
	s_waitcnt vmcnt(28)
	s_branch .Lqk_go_8
.Lqk_n7_8:
	s_cmp_gt_i32 s16, 14
	s_cbranch_scc0 .Lqk_n6_8
	s_waitcnt vmcnt(24)
	s_branch .Lqk_go_8

; __device__ __forceinline__ void dsa_unit(int wv, const Args& A, LAS unsigned char* lds, int s, int qt) {
;     ...
;         for (int kt = 0; kt < nt; ++kt) {
;             long k1[8];
;             DSA_LOADT(k1, kt + 1);
;             f32x4 a = {0.f, 0.f, 0.f, 0.f};
; #pragma unroll
;             for (int kk = 0; kk < 8; ++kk) a = __builtin_amdgcn_mfma_f32_16x16x32_fp8_fp8(kf[kk], qf[kk], a, 0, 0, 0);
;             if (fr < 8) {
; #pragma unroll
;                 for (int r = 0; r < 4; ++r) { const int e2 = kt * 16 + fq * 4 + r; const int key2 = lst[e2];
;                     Pw[e2 * 8 + fr] = (h16)(a[r] * 0.0625f + relb[rel_bucket(key2 - qpos) * 8 + fr]); } }
; #pragma unroll
;             for (int kk = 0; kk < 8; ++kk) kf[kk] = k1[kk];
.Lqk_go_8:
	v_mfma_f32_16x16x32_fp8_fp8 v[88:91], v[56:57], v[34:35], 0
	v_mfma_f32_16x16x32_fp8_fp8 v[88:91], v[58:59], v[32:33], v[88:91]
	v_mfma_f32_16x16x32_fp8_fp8 v[88:91], v[60:61], v[38:39], v[88:91]
	v_mfma_f32_16x16x32_fp8_fp8 v[88:91], v[62:63], v[36:37], v[88:91]
	v_mfma_f32_16x16x32_fp8_fp8 v[88:91], v[64:65], v[42:43], v[88:91]
	v_mfma_f32_16x16x32_fp8_fp8 v[88:91], v[66:67], v[40:41], v[88:91]
	v_mfma_f32_16x16x32_fp8_fp8 v[88:91], v[68:69], v[46:47], v[88:91]
	v_mfma_f32_16x16x32_fp8_fp8 v[88:91], v[70:71], v[44:45], v[88:91]
	s_and_saveexec_b64 s[12:13], s[8:9]
	s_waitcnt lgkmcnt(0)
	v_add_u32_e32 v165, v52, v25
	v_add_u32_e32 v166, v53, v25
	v_add_u32_e32 v167, v54, v25
	v_add_u32_e32 v168, v55, v25
	ds_read_b32 v165, v165
	ds_read_b32 v166, v166
	ds_read_b32 v167, v167
	ds_read_b32 v168, v168
	s_waitcnt lgkmcnt(3)
	v_fma_mixlo_f16 v165, v88, s3, v165
	s_waitcnt lgkmcnt(2)
	v_fma_mixlo_f16 v166, v89, s3, v166
	s_waitcnt lgkmcnt(1)
	v_fma_mixlo_f16 v167, v90, s3, v167
	s_waitcnt lgkmcnt(0)
	v_fma_mixlo_f16 v168, v91, s3, v168
	ds_write_b16 v143, v165 offset:2048
	ds_write_b16 v143, v166 offset:2064
	ds_write_b16 v143, v167 offset:2080
	ds_write_b16 v143, v168 offset:2096
	s_mov_b64 exec, s[12:13]
	s_cmp_le_i32 s16, 9
	s_cbranch_scc1 .Lqk_done
	ds_read_b128 v[52:55], v29 offset:576
	s_cmp_gt_i32 s16, 15
	s_cbranch_scc0 .Lqk_n6_9
	s_waitcnt vmcnt(24)
	s_branch .Lqk_go_9

; __device__ __forceinline__ void dsa_unit(int wv, const Args& A, LAS unsigned char* lds, int s, int qt) {
;     ...
;         for (int kt = 0; kt < nt; ++kt) {
;             long k1[8];
;             DSA_LOADT(k1, kt + 1);
;             f32x4 a = {0.f, 0.f, 0.f, 0.f};
; #pragma unroll
;             for (int kk = 0; kk < 8; ++kk) a = __builtin_amdgcn_mfma_f32_16x16x32_fp8_fp8(kf[kk], qf[kk], a, 0, 0, 0);
;             if (fr < 8) {
; #pragma unroll
;                 for (int r = 0; r < 4; ++r) { const int e2 = kt * 16 + fq * 4 + r; const int key2 = lst[e2];
;                     Pw[e2 * 8 + fr] = (h16)(a[r] * 0.0625f + relb[rel_bucket(key2 - qpos) * 8 + fr]); } }
; #pragma unroll
;             for (int kk = 0; kk < 8; ++kk) kf[kk] = k1[kk];
.Lqk_go_9:
	v_mfma_f32_16x16x32_fp8_fp8 v[88:91], v[72:73], v[34:35], 0
	v_mfma_f32_16x16x32_fp8_fp8 v[88:91], v[74:75], v[32:33], v[88:91]
	v_mfma_f32_16x16x32_fp8_fp8 v[88:91], v[76:77], v[38:39], v[88:91]
	v_mfma_f32_16x16x32_fp8_fp8 v[88:91], v[78:79], v[36:37], v[88:91]
	v_mfma_f32_16x16x32_fp8_fp8 v[88:91], v[80:81], v[42:43], v[88:91]
	v_mfma_f32_16x16x32_fp8_fp8 v[88:91], v[82:83], v[40:41], v[88:91]
	v_mfma_f32_16x16x32_fp8_fp8 v[88:91], v[84:85], v[46:47], v[88:91]
	v_mfma_f32_16x16x32_fp8_fp8 v[88:91], v[86:87], v[44:45], v[88:91]
	s_and_saveexec_b64 s[12:13], s[8:9]
	s_waitcnt lgkmcnt(0)
	v_add_u32_e32 v165, v52, v25
	v_add_u32_e32 v166, v53, v25
	v_add_u32_e32 v167, v54, v25
	v_add_u32_e32 v168, v55, v25
	ds_read_b32 v165, v165
	ds_read_b32 v166, v166
	ds_read_b32 v167, v167
	ds_read_b32 v168, v168
	s_waitcnt lgkmcnt(3)
	v_fma_mixlo_f16 v165, v88, s3, v165
	s_waitcnt lgkmcnt(2)
	v_fma_mixlo_f16 v166, v89, s3, v166
	s_waitcnt lgkmcnt(1)
	v_fma_mixlo_f16 v167, v90, s3, v167
	s_waitcnt lgkmcnt(0)
	v_fma_mixlo_f16 v168, v91, s3, v168
	ds_write_b16 v143, v165 offset:2304
	ds_write_b16 v143, v166 offset:2320
	ds_write_b16 v143, v167 offset:2336
	ds_write_b16 v143, v168 offset:2352
	s_mov_b64 exec, s[12:13]
	s_cmp_le_i32 s16, 10
	s_cbranch_scc1 .Lqk_done
	ds_read_b128 v[52:55], v29 offset:640
	s_cmp_gt_i32 s16, 15
	s_cbranch_scc0 .Lqk_n5_10
	s_waitcnt vmcnt(20)
	s_branch .Lqk_go_10

; __device__ __forceinline__ void dsa_unit(int wv, const Args& A, LAS unsigned char* lds, int s, int qt) {
;     ...
;         for (int kt = 0; kt < nt; ++kt) {
;             long k1[8];
;             DSA_LOADT(k1, kt + 1);
;             f32x4 a = {0.f, 0.f, 0.f, 0.f};
; #pragma unroll
;             for (int kk = 0; kk < 8; ++kk) a = __builtin_amdgcn_mfma_f32_16x16x32_fp8_fp8(kf[kk], qf[kk], a, 0, 0, 0);
;             if (fr < 8) {
; #pragma unroll
;                 for (int r = 0; r < 4; ++r) { const int e2 = kt * 16 + fq * 4 + r; const int key2 = lst[e2];
;                     Pw[e2 * 8 + fr] = (h16)(a[r] * 0.0625f + relb[rel_bucket(key2 - qpos) * 8 + fr]); } }
; #pragma unroll
;             for (int kk = 0; kk < 8; ++kk) kf[kk] = k1[kk];
.Lqk_go_10:
	v_mfma_f32_16x16x32_fp8_fp8 v[88:91], v[124:125], v[34:35], 0
	v_mfma_f32_16x16x32_fp8_fp8 v[88:91], v[126:127], v[32:33], v[88:91]
	v_mfma_f32_16x16x32_fp8_fp8 v[88:91], v[128:129], v[38:39], v[88:91]
	v_mfma_f32_16x16x32_fp8_fp8 v[88:91], v[130:131], v[36:37], v[88:91]
	v_mfma_f32_16x16x32_fp8_fp8 v[88:91], v[132:133], v[42:43], v[88:91]
	v_mfma_f32_16x16x32_fp8_fp8 v[88:91], v[134:135], v[40:41], v[88:91]
	v_mfma_f32_16x16x32_fp8_fp8 v[88:91], v[136:137], v[46:47], v[88:91]
	v_mfma_f32_16x16x32_fp8_fp8 v[88:91], v[138:139], v[44:45], v[88:91]
	s_and_saveexec_b64 s[12:13], s[8:9]
	s_waitcnt lgkmcnt(0)
	v_add_u32_e32 v165, v52, v25
	v_add_u32_e32 v166, v53, v25
	v_add_u32_e32 v167, v54, v25
	v_add_u32_e32 v168, v55, v25
	ds_read_b32 v165, v165
	ds_read_b32 v166, v166
	ds_read_b32 v167, v167
	ds_read_b32 v168, v168
	s_waitcnt lgkmcnt(3)
	v_fma_mixlo_f16 v165, v88, s3, v165
	s_waitcnt lgkmcnt(2)
	v_fma_mixlo_f16 v166, v89, s3, v166
	s_waitcnt lgkmcnt(1)
	v_fma_mixlo_f16 v167, v90, s3, v167
	s_waitcnt lgkmcnt(0)
	v_fma_mixlo_f16 v168, v91, s3, v168
	ds_write_b16 v143, v165 offset:2560
	ds_write_b16 v143, v166 offset:2576
	ds_write_b16 v143, v167 offset:2592
	ds_write_b16 v143, v168 offset:2608
	s_mov_b64 exec, s[12:13]
	s_cmp_le_i32 s16, 11
	s_cbranch_scc1 .Lqk_done
	ds_read_b128 v[52:55], v29 offset:704
	s_cmp_gt_i32 s16, 15
	s_cbranch_scc0 .Lqk_n4_11
	s_waitcnt vmcnt(16)
	s_branch .Lqk_go_11

; __device__ __forceinline__ void dsa_unit(int wv, const Args& A, LAS unsigned char* lds, int s, int qt) {
;     ...
;         for (int kt = 0; kt < nt; ++kt) {
;             long k1[8];
;             DSA_LOADT(k1, kt + 1);
;             f32x4 a = {0.f, 0.f, 0.f, 0.f};
; #pragma unroll
;             for (int kk = 0; kk < 8; ++kk) a = __builtin_amdgcn_mfma_f32_16x16x32_fp8_fp8(kf[kk], qf[kk], a, 0, 0, 0);
;             if (fr < 8) {
; #pragma unroll
;                 for (int r = 0; r < 4; ++r) { const int e2 = kt * 16 + fq * 4 + r; const int key2 = lst[e2];
;                     Pw[e2 * 8 + fr] = (h16)(a[r] * 0.0625f + relb[rel_bucket(key2 - qpos) * 8 + fr]); } }
; #pragma unroll
;             for (int kk = 0; kk < 8; ++kk) kf[kk] = k1[kk];
.Lqk_go_11:
	v_mfma_f32_16x16x32_fp8_fp8 v[88:91], v[180:181], v[34:35], 0
	v_mfma_f32_16x16x32_fp8_fp8 v[88:91], v[182:183], v[32:33], v[88:91]
	v_mfma_f32_16x16x32_fp8_fp8 v[88:91], v[184:185], v[38:39], v[88:91]
	v_mfma_f32_16x16x32_fp8_fp8 v[88:91], v[186:187], v[36:37], v[88:91]
	v_mfma_f32_16x16x32_fp8_fp8 v[88:91], v[188:189], v[42:43], v[88:91]
	v_mfma_f32_16x16x32_fp8_fp8 v[88:91], v[190:191], v[40:41], v[88:91]
	v_mfma_f32_16x16x32_fp8_fp8 v[88:91], v[192:193], v[46:47], v[88:91]
	v_mfma_f32_16x16x32_fp8_fp8 v[88:91], v[194:195], v[44:45], v[88:91]
	s_and_saveexec_b64 s[12:13], s[8:9]
	s_waitcnt lgkmcnt(0)
	v_add_u32_e32 v165, v52, v25
	v_add_u32_e32 v166, v53, v25
	v_add_u32_e32 v167, v54, v25
	v_add_u32_e32 v168, v55, v25
	ds_read_b32 v165, v165
	ds_read_b32 v166, v166
	ds_read_b32 v167, v167
	ds_read_b32 v168, v168
	s_waitcnt lgkmcnt(3)
	v_fma_mixlo_f16 v165, v88, s3, v165
	s_waitcnt lgkmcnt(2)
	v_fma_mixlo_f16 v166, v89, s3, v166
	s_waitcnt lgkmcnt(1)
	v_fma_mixlo_f16 v167, v90, s3, v167
	s_waitcnt lgkmcnt(0)
	v_fma_mixlo_f16 v168, v91, s3, v168
	ds_write_b16 v143, v165 offset:2816
	ds_write_b16 v143, v166 offset:2832
	ds_write_b16 v143, v167 offset:2848
	ds_write_b16 v143, v168 offset:2864
	s_mov_b64 exec, s[12:13]
	s_cmp_le_i32 s16, 12
	s_cbranch_scc1 .Lqk_done
	ds_read_b128 v[52:55], v29 offset:768
	s_cmp_gt_i32 s16, 15
	s_cbranch_scc0 .Lqk_n3_12
	s_waitcnt vmcnt(12)
	s_branch .Lqk_go_12

; __device__ __forceinline__ void dsa_unit(int wv, const Args& A, LAS unsigned char* lds, int s, int qt) {
;     ...
;         for (int kt = 0; kt < nt; ++kt) {
;             long k1[8];
;             DSA_LOADT(k1, kt + 1);
;             f32x4 a = {0.f, 0.f, 0.f, 0.f};
; #pragma unroll
;             for (int kk = 0; kk < 8; ++kk) a = __builtin_amdgcn_mfma_f32_16x16x32_fp8_fp8(kf[kk], qf[kk], a, 0, 0, 0);
;             if (fr < 8) {
; #pragma unroll
;                 for (int r = 0; r < 4; ++r) { const int e2 = kt * 16 + fq * 4 + r; const int key2 = lst[e2];
;                     Pw[e2 * 8 + fr] = (h16)(a[r] * 0.0625f + relb[rel_bucket(key2 - qpos) * 8 + fr]); } }
; #pragma unroll
;             for (int kk = 0; kk < 8; ++kk) kf[kk] = k1[kk];
.Lqk_go_12:
	v_mfma_f32_16x16x32_fp8_fp8 v[88:91], v[196:197], v[34:35], 0
	v_mfma_f32_16x16x32_fp8_fp8 v[88:91], v[198:199], v[32:33], v[88:91]
	v_mfma_f32_16x16x32_fp8_fp8 v[88:91], v[200:201], v[38:39], v[88:91]
	v_mfma_f32_16x16x32_fp8_fp8 v[88:91], v[202:203], v[36:37], v[88:91]
	v_mfma_f32_16x16x32_fp8_fp8 v[88:91], v[204:205], v[42:43], v[88:91]
	v_mfma_f32_16x16x32_fp8_fp8 v[88:91], v[206:207], v[40:41], v[88:91]
	v_mfma_f32_16x16x32_fp8_fp8 v[88:91], v[208:209], v[46:47], v[88:91]
	v_mfma_f32_16x16x32_fp8_fp8 v[88:91], v[210:211], v[44:45], v[88:91]
	s_and_saveexec_b64 s[12:13], s[8:9]
	s_waitcnt lgkmcnt(0)
	v_add_u32_e32 v165, v52, v25
	v_add_u32_e32 v166, v53, v25
	v_add_u32_e32 v167, v54, v25
	v_add_u32_e32 v168, v55, v25
	ds_read_b32 v165, v165
	ds_read_b32 v166, v166
	ds_read_b32 v167, v167
	ds_read_b32 v168, v168
	s_waitcnt lgkmcnt(3)
	v_fma_mixlo_f16 v165, v88, s3, v165
	s_waitcnt lgkmcnt(2)
	v_fma_mixlo_f16 v166, v89, s3, v166
	s_waitcnt lgkmcnt(1)
	v_fma_mixlo_f16 v167, v90, s3, v167
	s_waitcnt lgkmcnt(0)
	v_fma_mixlo_f16 v168, v91, s3, v168
	ds_write_b16 v143, v165 offset:3072
	ds_write_b16 v143, v166 offset:3088
	ds_write_b16 v143, v167 offset:3104
	ds_write_b16 v143, v168 offset:3120
	s_mov_b64 exec, s[12:13]
	s_cmp_le_i32 s16, 13
	s_cbranch_scc1 .Lqk_done
	ds_read_b128 v[52:55], v29 offset:832
	s_cmp_gt_i32 s16, 15
	s_cbranch_scc0 .Lqk_n2_13
	s_waitcnt vmcnt(8)
	s_branch .Lqk_go_13

; __device__ __forceinline__ void dsa_unit(int wv, const Args& A, LAS unsigned char* lds, int s, int qt) {
;     ...
;         for (int kt = 0; kt < nt; ++kt) {
;             long k1[8];
;             DSA_LOADT(k1, kt + 1);
;             f32x4 a = {0.f, 0.f, 0.f, 0.f};
; #pragma unroll
;             for (int kk = 0; kk < 8; ++kk) a = __builtin_amdgcn_mfma_f32_16x16x32_fp8_fp8(kf[kk], qf[kk], a, 0, 0, 0);
;             if (fr < 8) {
; #pragma unroll
;                 for (int r = 0; r < 4; ++r) { const int e2 = kt * 16 + fq * 4 + r; const int key2 = lst[e2];
;                     Pw[e2 * 8 + fr] = (h16)(a[r] * 0.0625f + relb[rel_bucket(key2 - qpos) * 8 + fr]); } }
; #pragma unroll
;             for (int kk = 0; kk < 8; ++kk) kf[kk] = k1[kk];
.Lqk_go_13:
	v_mfma_f32_16x16x32_fp8_fp8 v[88:91], v[212:213], v[34:35], 0
	v_mfma_f32_16x16x32_fp8_fp8 v[88:91], v[214:215], v[32:33], v[88:91]
	v_mfma_f32_16x16x32_fp8_fp8 v[88:91], v[216:217], v[38:39], v[88:91]
	v_mfma_f32_16x16x32_fp8_fp8 v[88:91], v[218:219], v[36:37], v[88:91]
	v_mfma_f32_16x16x32_fp8_fp8 v[88:91], v[220:221], v[42:43], v[88:91]
	v_mfma_f32_16x16x32_fp8_fp8 v[88:91], v[222:223], v[40:41], v[88:91]
	v_mfma_f32_16x16x32_fp8_fp8 v[88:91], v[224:225], v[46:47], v[88:91]
	v_mfma_f32_16x16x32_fp8_fp8 v[88:91], v[226:227], v[44:45], v[88:91]
	s_and_saveexec_b64 s[12:13], s[8:9]
	s_waitcnt lgkmcnt(0)
	v_add_u32_e32 v165, v52, v25
	v_add_u32_e32 v166, v53, v25
	v_add_u32_e32 v167, v54, v25
	v_add_u32_e32 v168, v55, v25
	ds_read_b32 v165, v165
	ds_read_b32 v166, v166
	ds_read_b32 v167, v167
	ds_read_b32 v168, v168
	s_waitcnt lgkmcnt(3)
	v_fma_mixlo_f16 v165, v88, s3, v165
	s_waitcnt lgkmcnt(2)
	v_fma_mixlo_f16 v166, v89, s3, v166
	s_waitcnt lgkmcnt(1)
	v_fma_mixlo_f16 v167, v90, s3, v167
	s_waitcnt lgkmcnt(0)
	v_fma_mixlo_f16 v168, v91, s3, v168
	ds_write_b16 v143, v165 offset:3328
	ds_write_b16 v143, v166 offset:3344
	ds_write_b16 v143, v167 offset:3360
	ds_write_b16 v143, v168 offset:3376
	s_mov_b64 exec, s[12:13]
	s_cmp_le_i32 s16, 14
	s_cbranch_scc1 .Lqk_done
	ds_read_b128 v[52:55], v29 offset:896
	s_cmp_gt_i32 s16, 15
	s_cbranch_scc0 .Lqk_n1_14
	s_waitcnt vmcnt(4)
	s_branch .Lqk_go_14

; __device__ __forceinline__ void dsa_unit(int wv, const Args& A, LAS unsigned char* lds, int s, int qt) {
;     ...
;         for (int kt = 0; kt < nt; ++kt) {
;             long k1[8];
;             DSA_LOADT(k1, kt + 1);
;             f32x4 a = {0.f, 0.f, 0.f, 0.f};
; #pragma unroll
;             for (int kk = 0; kk < 8; ++kk) a = __builtin_amdgcn_mfma_f32_16x16x32_fp8_fp8(kf[kk], qf[kk], a, 0, 0, 0);
;             if (fr < 8) {
; #pragma unroll
;                 for (int r = 0; r < 4; ++r) { const int e2 = kt * 16 + fq * 4 + r; const int key2 = lst[e2];
;                     Pw[e2 * 8 + fr] = (h16)(a[r] * 0.0625f + relb[rel_bucket(key2 - qpos) * 8 + fr]); } }
; #pragma unroll
;             for (int kk = 0; kk < 8; ++kk) kf[kk] = k1[kk];
.Lqk_go_14:
	v_mfma_f32_16x16x32_fp8_fp8 v[88:91], v[240:241], v[34:35], 0
	v_mfma_f32_16x16x32_fp8_fp8 v[88:91], v[242:243], v[32:33], v[88:91]
	v_mfma_f32_16x16x32_fp8_fp8 v[88:91], v[244:245], v[38:39], v[88:91]
	v_mfma_f32_16x16x32_fp8_fp8 v[88:91], v[246:247], v[36:37], v[88:91]
	v_mfma_f32_16x16x32_fp8_fp8 v[88:91], v[248:249], v[42:43], v[88:91]
	v_mfma_f32_16x16x32_fp8_fp8 v[88:91], v[250:251], v[40:41], v[88:91]
	v_mfma_f32_16x16x32_fp8_fp8 v[88:91], v[252:253], v[46:47], v[88:91]
	v_mfma_f32_16x16x32_fp8_fp8 v[88:91], v[254:255], v[44:45], v[88:91]
	s_and_saveexec_b64 s[12:13], s[8:9]
	s_waitcnt lgkmcnt(0)
	v_add_u32_e32 v165, v52, v25
	v_add_u32_e32 v166, v53, v25
	v_add_u32_e32 v167, v54, v25
	v_add_u32_e32 v168, v55, v25
	ds_read_b32 v165, v165
	ds_read_b32 v166, v166
	ds_read_b32 v167, v167
	ds_read_b32 v168, v168
	s_waitcnt lgkmcnt(3)
	v_fma_mixlo_f16 v165, v88, s3, v165
	s_waitcnt lgkmcnt(2)
	v_fma_mixlo_f16 v166, v89, s3, v166
	s_waitcnt lgkmcnt(1)
	v_fma_mixlo_f16 v167, v90, s3, v167
	s_waitcnt lgkmcnt(0)
	v_fma_mixlo_f16 v168, v91, s3, v168
	ds_write_b16 v143, v165 offset:3584
	ds_write_b16 v143, v166 offset:3600
	ds_write_b16 v143, v167 offset:3616
	ds_write_b16 v143, v168 offset:3632
	s_mov_b64 exec, s[12:13]
	s_cmp_le_i32 s16, 15
	s_cbranch_scc1 .Lqk_done
	ds_read_b128 v[52:55], v29 offset:960
	s_waitcnt vmcnt(0)
.Lqk_go_15:
	v_mfma_f32_16x16x32_fp8_fp8 v[88:91], v[4:5], v[34:35], 0
	v_mfma_f32_16x16x32_fp8_fp8 v[88:91], v[6:7], v[32:33], v[88:91]
	v_mfma_f32_16x16x32_fp8_fp8 v[88:91], v[8:9], v[38:39], v[88:91]
	v_mfma_f32_16x16x32_fp8_fp8 v[88:91], v[10:11], v[36:37], v[88:91]
	v_mfma_f32_16x16x32_fp8_fp8 v[88:91], v[12:13], v[42:43], v[88:91]
	v_mfma_f32_16x16x32_fp8_fp8 v[88:91], v[14:15], v[40:41], v[88:91]
	v_mfma_f32_16x16x32_fp8_fp8 v[88:91], v[16:17], v[46:47], v[88:91]
	v_mfma_f32_16x16x32_fp8_fp8 v[88:91], v[18:19], v[44:45], v[88:91]
	s_and_saveexec_b64 s[12:13], s[8:9]
	s_waitcnt lgkmcnt(0)
	v_add_u32_e32 v165, v52, v25
	v_add_u32_e32 v166, v53, v25
	v_add_u32_e32 v167, v54, v25
	v_add_u32_e32 v168, v55, v25
	ds_read_b32 v165, v165
	ds_read_b32 v166, v166
	ds_read_b32 v167, v167
	ds_read_b32 v168, v168
	s_waitcnt lgkmcnt(3)
	v_fma_mixlo_f16 v165, v88, s3, v165
	s_waitcnt lgkmcnt(2)
	v_fma_mixlo_f16 v166, v89, s3, v166
	s_waitcnt lgkmcnt(1)
	v_fma_mixlo_f16 v167, v90, s3, v167
	s_waitcnt lgkmcnt(0)
	v_fma_mixlo_f16 v168, v91, s3, v168
	ds_write_b16 v143, v165 offset:3840
	ds_write_b16 v143, v166 offset:3856
	ds_write_b16 v143, v167 offset:3872
	ds_write_b16 v143, v168 offset:3888
	s_mov_b64 exec, s[12:13]
